# phase A epilogue: hand-written path extended to the rope (64/16-wide) column groups with q scaling and the compact K/V copy, cos/sin rows of a pass loaded up-front into the idle second register stage;
# speedup vs baseline: 1.1618x; 1.0062x over previous
.Ltpa_30:
	s_cmp_eq_u32 s6, 30
	s_cbranch_scc0 .Ltpa_18
	s_add_i32 s7, s7, -24
	s_branch .Ltpa_done
.Ltpa_18:
	s_cmp_eq_u32 s6, 18
	s_cbranch_scc0 .Ltpa_19
	s_add_i32 s7, s7, 8
	s_branch .Ltpa_done
.Ltpa_19:
	s_cmp_eq_u32 s6, 19
	s_cbranch_scc0 .Ltpa_done
	s_add_i32 s7, s7, -8

.Ltpb_30:
	s_cmp_eq_u32 s3, 30
	s_cbranch_scc0 .Ltpb_18
	s_add_i32 s2, s2, -24
	s_branch .Ltpb_done
.Ltpb_18:
	s_cmp_eq_u32 s3, 18
	s_cbranch_scc0 .Ltpb_19
	s_add_i32 s2, s2, 8
	s_branch .Ltpb_done
.Ltpb_19:
	s_cmp_eq_u32 s3, 19
	s_cbranch_scc0 .Ltpb_done
	s_add_i32 s2, s2, -8

.LBB0_350:
	v_readfirstlane_b32 s2, v30
	s_lshr_b32 s2, s2, 7
	s_lshl_b32 s3, s48, 1
	s_add_i32 s3, s3, s2
	s_cmp_eq_u32 s3, 61
	s_cbranch_scc1 .LBB0_341
	s_mov_b32 s6, 0xffffffff
	s_mov_b32 s7, 0xfffffef
	s_lshr_b64 s[6:7], s[6:7], s3
	s_bitcmp1_b32 s6, 0
	s_cbranch_scc0 .Lep_slow
	s_lshl_b32 s31, s3, 1
	s_mov_b32 s28, 0x3e000000
	s_mov_b32 s29, 1.0
	s_mov_b32 s12, 0x1e800
	s_mov_b32 s13, 0
	s_movk_i32 s14, 0x80
	s_mov_b32 s15, 0
	s_mov_b32 s16, 0xbfb8aa3b
	s_mov_b32 s17, s16
	s_lshl_b32 s50, s8, 8
	v_add_u32_e32 v184, s50, v46
	s_movk_i32 s8, 0x6000
	s_mov_b32 s9, 0
	s_lshl_b32 s6, s48, 8
	v_or3_b32 v2, s6, v30, v31
	v_mov_b32_e32 v3, 0
	v_lshl_add_u64 v[4:5], v[2:3], 1, s[56:57]
	v_mad_u64_u32 v[178:179], s[6:7], v184, s68, v[4:5]
	v_mov_b32_e32 v185, 0
	s_add_i32 s2, s31, 0
	s_cmp_ge_u32 s2, 0x4a
	s_cselect_b32 s51, 2, 0
	s_sub_i32 s6, s2, 16
	s_cmp_lt_u32 s6, 8
	s_cselect_b32 s51, 1, s51
	s_sub_i32 s6, s2, 36
	s_cmp_lt_u32 s6, 8
	s_cselect_b32 s51, 1, s51
	s_sub_i32 s6, s2, 65
	s_cmp_lt_u32 s6, 8
	s_cselect_b32 s51, 1, s51
	s_mov_b32 s10, s29
	s_sub_i32 s6, s2, 0
	s_cmp_lt_u32 s6, 4
	s_cselect_b32 s10, s28, s10
	s_sub_i32 s6, s2, 24
	s_cmp_lt_u32 s6, 8
	s_cselect_b32 s10, s28, s10
	s_sub_i32 s6, s2, 44
	s_cmp_lt_u32 s6, 4
	s_cselect_b32 s10, s28, s10
	s_sub_i32 s6, s2, 49
	s_cmp_lt_u32 s6, 4
	s_cselect_b32 s10, s28, s10
	s_mov_b32 s11, s10
	v_mov_b64_e32 v[172:173], v[178:179]
	s_cmp_lt_u32 s2, 8
	s_cbranch_scc0 .Lep_nr64_0
	s_movk_i32 s51, 3
	s_mov_b64 s[34:35], -1
	v_cmp_gt_u32_e64 s[36:37], 32, v31
	v_xor_b32_e32 v185, 32, v31
	v_lshl_add_u32 v185, v185, 2, v47
	v_lshlrev_b32_e32 v250, 8, v184
	v_mov_b32_e32 v251, 0
	v_lshl_add_u64 v[180:181], v[250:251], 0, v[12:13]
	s_movk_i32 s38, 0x800
	s_mov_b32 s39, 0
	s_branch .Lep_setdone_0
.Lep_nr64_0:
	s_sub_i32 s6, s2, 24
	s_cmp_lt_u32 s6, 10
	s_cselect_b32 s7, 1, 0
	s_sub_i32 s6, s2, 44
	s_cmp_lt_u32 s6, 5
	s_cselect_b32 s7, 1, s7
	s_cmp_eq_u32 s7, 0
	s_cbranch_scc1 .Lep_nr16_0
	s_movk_i32 s51, 3
	v_cmp_gt_u32_e64 s[34:35], 16, v31
	v_cmp_gt_u32_e64 s[36:37], 8, v31
	v_xor_b32_e32 v185, 8, v31
	v_lshl_add_u32 v185, v185, 2, v47
	v_lshlrev_b32_e32 v250, 6, v184
	v_mov_b32_e32 v251, 0
	v_lshl_add_u64 v[180:181], v[250:251], 0, s[0:1]
	s_movk_i32 s38, 0x200
	s_mov_b32 s39, 0
.Lep_nr16_0:
	s_sub_i32 s6, s2, 32
	s_cmp_lt_u32 s6, 4
	s_cselect_b32 s7, 1, 0
	s_lshl_b32 s6, s6, 7
	s_cmp_eq_u32 s2, 48
	s_cselect_b32 s7, 1, s7
	s_cselect_b32 s6, 0x200, s6
	s_cmp_eq_u32 s7, 0
	s_cbranch_scc1 .Lep_setdone_0
	s_cmp_eq_u32 s51, 3
	s_cselect_b32 s51, 4, 5
	v_lshl_add_u32 v250, v31, 1, s6
	v_mov_b32_e32 v251, 0
	v_lshl_add_u64 v[250:251], v[250:251], 0, s[96:97]
	v_mad_u64_u32 v[182:183], s[6:7], v184, s64, v[250:251]
.Lep_setdone_0:
	s_cmp_lt_u32 s51, 3
	s_cbranch_scc1 .Lep_go
	s_waitcnt vmcnt(0)
	s_branch .Lep_go
.Lep_go:
	s_cmp_eq_u32 s51, 3
	s_cselect_b32 s6, 1, 0
	s_cmp_eq_u32 s51, 4
	s_cselect_b32 s6, 1, s6
	s_cmp_eq_u32 s6, 0
	s_cbranch_scc1 .Lep_nt0
	v_mov_b64_e32 v[250:251], v[180:181]
	global_load_dwordx4 v[186:189], v[250:251], off
	global_load_dwordx4 v[190:193], v[250:251], off offset:16
	global_load_dwordx4 v[194:197], v[250:251], off offset:32
	global_load_dwordx4 v[198:201], v[250:251], off offset:48
	v_lshl_add_u64 v[250:251], v[250:251], 0, s[38:39]
	global_load_dwordx4 v[202:205], v[250:251], off
	global_load_dwordx4 v[206:209], v[250:251], off offset:16
	global_load_dwordx4 v[210:213], v[250:251], off offset:32
	global_load_dwordx4 v[214:217], v[250:251], off offset:48
	v_lshl_add_u64 v[250:251], v[250:251], 0, s[38:39]
	global_load_dwordx4 v[218:221], v[250:251], off
	global_load_dwordx4 v[222:225], v[250:251], off offset:16
	global_load_dwordx4 v[226:229], v[250:251], off offset:32
	global_load_dwordx4 v[230:233], v[250:251], off offset:48
	v_lshl_add_u64 v[250:251], v[250:251], 0, s[38:39]
	global_load_dwordx4 v[234:237], v[250:251], off
	global_load_dwordx4 v[238:241], v[250:251], off offset:16
	global_load_dwordx4 v[242:245], v[250:251], off offset:32
	global_load_dwordx4 v[246:249], v[250:251], off offset:48
	v_lshl_add_u64 v[250:251], v[250:251], 0, s[38:39]
	v_mov_b64_e32 v[180:181], v[250:251]
.Lep_nt0:
	ds_write_b32 v32, a224
	ds_write_b32 v33, a240
	ds_write_b32 v32, a225 offset:272
	ds_write_b32 v33, a241 offset:272
	ds_write_b32 v32, a226 offset:544
	ds_write_b32 v33, a242 offset:544
	ds_write_b32 v32, a227 offset:816
	ds_write_b32 v33, a243 offset:816
	ds_write_b32 v32, a228 offset:2176
	ds_write_b32 v33, a244 offset:2176
	ds_write_b32 v32, a229 offset:2448
	ds_write_b32 v33, a245 offset:2448
	ds_write_b32 v32, a230 offset:2720
	ds_write_b32 v33, a246 offset:2720
	ds_write_b32 v32, a231 offset:2992
	ds_write_b32 v33, a247 offset:2992
	ds_write_b32 v32, a232 offset:4352
	ds_write_b32 v33, a248 offset:4352
	ds_write_b32 v32, a233 offset:4624
	ds_write_b32 v33, a249 offset:4624
	ds_write_b32 v32, a234 offset:4896
	ds_write_b32 v33, a250 offset:4896
	ds_write_b32 v32, a235 offset:5168
	ds_write_b32 v33, a251 offset:5168
	ds_write_b32 v32, a236 offset:6528
	ds_write_b32 v33, a252 offset:6528
	ds_write_b32 v32, a237 offset:6800
	ds_write_b32 v33, a253 offset:6800
	ds_write_b32 v32, a238 offset:7072
	ds_write_b32 v33, a254 offset:7072
	ds_write_b32 v32, a239 offset:7344
	ds_write_b32 v33, a255 offset:7344
	ds_read_b128 v[124:127], v48
	ds_read_b128 v[128:131], v48 offset:16
	ds_read_b128 v[132:135], v48 offset:2176
	ds_read_b128 v[136:139], v48 offset:2192
	ds_read_b128 v[140:143], v48 offset:4352
	ds_read_b128 v[144:147], v48 offset:4368
	ds_read_b128 v[148:151], v48 offset:6528
	ds_read_b128 v[152:155], v48 offset:6544
	ds_read_b128 v[0:3], v185
	ds_read_b128 v[4:7], v185 offset:16
	ds_read_b128 v[8:11], v185 offset:2176
	ds_read_b128 v[14:17], v185 offset:2192
	ds_read_b128 v[18:21], v185 offset:4352
	ds_read_b128 v[22:25], v185 offset:4368
	ds_read_b128 v[26:29], v185 offset:6528
	ds_read_b128 v[50:53], v185 offset:6544
	s_movk_i32 s49, 1
	s_branch .Lep_compute

.Lep_nt1:
	ds_write_b32 v32, a192
	ds_write_b32 v33, a208
	ds_write_b32 v32, a193 offset:272
	ds_write_b32 v33, a209 offset:272
	ds_write_b32 v32, a194 offset:544
	ds_write_b32 v33, a210 offset:544
	ds_write_b32 v32, a195 offset:816
	ds_write_b32 v33, a211 offset:816
	ds_write_b32 v32, a196 offset:2176
	ds_write_b32 v33, a212 offset:2176
	ds_write_b32 v32, a197 offset:2448
	ds_write_b32 v33, a213 offset:2448
	ds_write_b32 v32, a198 offset:2720
	ds_write_b32 v33, a214 offset:2720
	ds_write_b32 v32, a199 offset:2992
	ds_write_b32 v33, a215 offset:2992
	ds_write_b32 v32, a200 offset:4352
	ds_write_b32 v33, a216 offset:4352
	ds_write_b32 v32, a201 offset:4624
	ds_write_b32 v33, a217 offset:4624
	ds_write_b32 v32, a202 offset:4896
	ds_write_b32 v33, a218 offset:4896
	ds_write_b32 v32, a203 offset:5168
	ds_write_b32 v33, a219 offset:5168
	ds_write_b32 v32, a204 offset:6528
	ds_write_b32 v33, a220 offset:6528
	ds_write_b32 v32, a205 offset:6800
	ds_write_b32 v33, a221 offset:6800
	ds_write_b32 v32, a206 offset:7072
	ds_write_b32 v33, a222 offset:7072
	ds_write_b32 v32, a207 offset:7344
	ds_write_b32 v33, a223 offset:7344
	ds_read_b128 v[124:127], v48
	ds_read_b128 v[128:131], v48 offset:16
	ds_read_b128 v[132:135], v48 offset:2176
	ds_read_b128 v[136:139], v48 offset:2192
	ds_read_b128 v[140:143], v48 offset:4352
	ds_read_b128 v[144:147], v48 offset:4368
	ds_read_b128 v[148:151], v48 offset:6528
	ds_read_b128 v[152:155], v48 offset:6544
	ds_read_b128 v[0:3], v185
	ds_read_b128 v[4:7], v185 offset:16
	ds_read_b128 v[8:11], v185 offset:2176
	ds_read_b128 v[14:17], v185 offset:2192
	ds_read_b128 v[18:21], v185 offset:4352
	ds_read_b128 v[22:25], v185 offset:4368
	ds_read_b128 v[26:29], v185 offset:6528
	ds_read_b128 v[50:53], v185 offset:6544
	s_movk_i32 s49, 2
	s_branch .Lep_compute

.Lep_nt2:
	ds_write_b32 v32, a160
	ds_write_b32 v33, a176
	ds_write_b32 v32, a161 offset:272
	ds_write_b32 v33, a177 offset:272
	ds_write_b32 v32, a162 offset:544
	ds_write_b32 v33, a178 offset:544
	ds_write_b32 v32, a163 offset:816
	ds_write_b32 v33, a179 offset:816
	ds_write_b32 v32, a164 offset:2176
	ds_write_b32 v33, a180 offset:2176
	ds_write_b32 v32, a165 offset:2448
	ds_write_b32 v33, a181 offset:2448
	ds_write_b32 v32, a166 offset:2720
	ds_write_b32 v33, a182 offset:2720
	ds_write_b32 v32, a167 offset:2992
	ds_write_b32 v33, a183 offset:2992
	ds_write_b32 v32, a168 offset:4352
	ds_write_b32 v33, a184 offset:4352
	ds_write_b32 v32, a169 offset:4624
	ds_write_b32 v33, a185 offset:4624
	ds_write_b32 v32, a170 offset:4896
	ds_write_b32 v33, a186 offset:4896
	ds_write_b32 v32, a171 offset:5168
	ds_write_b32 v33, a187 offset:5168
	ds_write_b32 v32, a172 offset:6528
	ds_write_b32 v33, a188 offset:6528
	ds_write_b32 v32, a173 offset:6800
	ds_write_b32 v33, a189 offset:6800
	ds_write_b32 v32, a174 offset:7072
	ds_write_b32 v33, a190 offset:7072
	ds_write_b32 v32, a175 offset:7344
	ds_write_b32 v33, a191 offset:7344
	ds_read_b128 v[124:127], v48
	ds_read_b128 v[128:131], v48 offset:16
	ds_read_b128 v[132:135], v48 offset:2176
	ds_read_b128 v[136:139], v48 offset:2192
	ds_read_b128 v[140:143], v48 offset:4352
	ds_read_b128 v[144:147], v48 offset:4368
	ds_read_b128 v[148:151], v48 offset:6528
	ds_read_b128 v[152:155], v48 offset:6544
	ds_read_b128 v[0:3], v185
	ds_read_b128 v[4:7], v185 offset:16
	ds_read_b128 v[8:11], v185 offset:2176
	ds_read_b128 v[14:17], v185 offset:2192
	ds_read_b128 v[18:21], v185 offset:4352
	ds_read_b128 v[22:25], v185 offset:4368
	ds_read_b128 v[26:29], v185 offset:6528
	ds_read_b128 v[50:53], v185 offset:6544
	s_movk_i32 s49, 3
	s_branch .Lep_compute

.Lep_nt3:
	ds_write_b32 v32, a128
	ds_write_b32 v33, a144
	ds_write_b32 v32, a129 offset:272
	ds_write_b32 v33, a145 offset:272
	ds_write_b32 v32, a130 offset:544
	ds_write_b32 v33, a146 offset:544
	ds_write_b32 v32, a131 offset:816
	ds_write_b32 v33, a147 offset:816
	ds_write_b32 v32, a132 offset:2176
	ds_write_b32 v33, a148 offset:2176
	ds_write_b32 v32, a133 offset:2448
	ds_write_b32 v33, a149 offset:2448
	ds_write_b32 v32, a134 offset:2720
	ds_write_b32 v33, a150 offset:2720
	ds_write_b32 v32, a135 offset:2992
	ds_write_b32 v33, a151 offset:2992
	ds_write_b32 v32, a136 offset:4352
	ds_write_b32 v33, a152 offset:4352
	ds_write_b32 v32, a137 offset:4624
	ds_write_b32 v33, a153 offset:4624
	ds_write_b32 v32, a138 offset:4896
	ds_write_b32 v33, a154 offset:4896
	ds_write_b32 v32, a139 offset:5168
	ds_write_b32 v33, a155 offset:5168
	ds_write_b32 v32, a140 offset:6528
	ds_write_b32 v33, a156 offset:6528
	ds_write_b32 v32, a141 offset:6800
	ds_write_b32 v33, a157 offset:6800
	ds_write_b32 v32, a142 offset:7072
	ds_write_b32 v33, a158 offset:7072
	ds_write_b32 v32, a143 offset:7344
	ds_write_b32 v33, a159 offset:7344
	ds_read_b128 v[124:127], v48
	ds_read_b128 v[128:131], v48 offset:16
	ds_read_b128 v[132:135], v48 offset:2176
	ds_read_b128 v[136:139], v48 offset:2192
	ds_read_b128 v[140:143], v48 offset:4352
	ds_read_b128 v[144:147], v48 offset:4368
	ds_read_b128 v[148:151], v48 offset:6528
	ds_read_b128 v[152:155], v48 offset:6544
	ds_read_b128 v[0:3], v185
	ds_read_b128 v[4:7], v185 offset:16
	ds_read_b128 v[8:11], v185 offset:2176
	ds_read_b128 v[14:17], v185 offset:2192
	ds_read_b128 v[18:21], v185 offset:4352
	ds_read_b128 v[22:25], v185 offset:4368
	ds_read_b128 v[26:29], v185 offset:6528
	ds_read_b128 v[50:53], v185 offset:6544
	s_movk_i32 s49, 4
	s_branch .Lep_compute
.Lep_p4:
	s_add_i32 s2, s31, 1
	s_cmp_ge_u32 s2, 0x4a
	s_cselect_b32 s51, 2, 0
	s_sub_i32 s6, s2, 16
	s_cmp_lt_u32 s6, 8
	s_cselect_b32 s51, 1, s51
	s_sub_i32 s6, s2, 36
	s_cmp_lt_u32 s6, 8
	s_cselect_b32 s51, 1, s51
	s_sub_i32 s6, s2, 65
	s_cmp_lt_u32 s6, 8
	s_cselect_b32 s51, 1, s51
	s_mov_b32 s10, s29
	s_sub_i32 s6, s2, 0
	s_cmp_lt_u32 s6, 4
	s_cselect_b32 s10, s28, s10
	s_sub_i32 s6, s2, 24
	s_cmp_lt_u32 s6, 8
	s_cselect_b32 s10, s28, s10
	s_sub_i32 s6, s2, 44
	s_cmp_lt_u32 s6, 4
	s_cselect_b32 s10, s28, s10
	s_sub_i32 s6, s2, 49
	s_cmp_lt_u32 s6, 4
	s_cselect_b32 s10, s28, s10
	s_mov_b32 s11, s10
	v_lshl_add_u64 v[172:173], v[178:179], 0, s[14:15]
	s_cmp_lt_u32 s2, 8
	s_cbranch_scc0 .Lep_nr64_1
	s_movk_i32 s51, 3
	s_mov_b64 s[34:35], -1
	v_cmp_gt_u32_e64 s[36:37], 32, v31
	v_xor_b32_e32 v185, 32, v31
	v_lshl_add_u32 v185, v185, 2, v47
	v_lshlrev_b32_e32 v250, 8, v184
	v_mov_b32_e32 v251, 0
	v_lshl_add_u64 v[180:181], v[250:251], 0, v[12:13]
	s_movk_i32 s38, 0x800
	s_mov_b32 s39, 0
	s_branch .Lep_setdone_1

.Lep_setdone_1:
	s_cmp_lt_u32 s51, 3
	s_cbranch_scc1 .Lep_go4
	s_waitcnt vmcnt(0)

.Lep_nt4:
	ds_write_b32 v32, a96
	ds_write_b32 v33, a112
	ds_write_b32 v32, a97 offset:272
	ds_write_b32 v33, a113 offset:272
	ds_write_b32 v32, a98 offset:544
	ds_write_b32 v33, a114 offset:544
	ds_write_b32 v32, a99 offset:816
	ds_write_b32 v33, a115 offset:816
	ds_write_b32 v32, a100 offset:2176
	ds_write_b32 v33, a116 offset:2176
	ds_write_b32 v32, a101 offset:2448
	ds_write_b32 v33, a117 offset:2448
	ds_write_b32 v32, a102 offset:2720
	ds_write_b32 v33, a118 offset:2720
	ds_write_b32 v32, a103 offset:2992
	ds_write_b32 v33, a119 offset:2992
	ds_write_b32 v32, a104 offset:4352
	ds_write_b32 v33, a120 offset:4352
	ds_write_b32 v32, a105 offset:4624
	ds_write_b32 v33, a121 offset:4624
	ds_write_b32 v32, a106 offset:4896
	ds_write_b32 v33, a122 offset:4896
	ds_write_b32 v32, a107 offset:5168
	ds_write_b32 v33, a123 offset:5168
	ds_write_b32 v32, a108 offset:6528
	ds_write_b32 v33, a124 offset:6528
	ds_write_b32 v32, a109 offset:6800
	ds_write_b32 v33, a125 offset:6800
	ds_write_b32 v32, a110 offset:7072
	ds_write_b32 v33, a126 offset:7072
	ds_write_b32 v32, a111 offset:7344
	ds_write_b32 v33, a127 offset:7344
	ds_read_b128 v[124:127], v48
	ds_read_b128 v[128:131], v48 offset:16
	ds_read_b128 v[132:135], v48 offset:2176
	ds_read_b128 v[136:139], v48 offset:2192
	ds_read_b128 v[140:143], v48 offset:4352
	ds_read_b128 v[144:147], v48 offset:4368
	ds_read_b128 v[148:151], v48 offset:6528
	ds_read_b128 v[152:155], v48 offset:6544
	ds_read_b128 v[0:3], v185
	ds_read_b128 v[4:7], v185 offset:16
	ds_read_b128 v[8:11], v185 offset:2176
	ds_read_b128 v[14:17], v185 offset:2192
	ds_read_b128 v[18:21], v185 offset:4352
	ds_read_b128 v[22:25], v185 offset:4368
	ds_read_b128 v[26:29], v185 offset:6528
	ds_read_b128 v[50:53], v185 offset:6544
	s_movk_i32 s49, 5
	s_branch .Lep_compute

.Lep_nt5:
	ds_write_b32 v32, a64
	ds_write_b32 v33, a80
	ds_write_b32 v32, a65 offset:272
	ds_write_b32 v33, a81 offset:272
	ds_write_b32 v32, a66 offset:544
	ds_write_b32 v33, a82 offset:544
	ds_write_b32 v32, a67 offset:816
	ds_write_b32 v33, a83 offset:816
	ds_write_b32 v32, a68 offset:2176
	ds_write_b32 v33, a84 offset:2176
	ds_write_b32 v32, a69 offset:2448
	ds_write_b32 v33, a85 offset:2448
	ds_write_b32 v32, a70 offset:2720
	ds_write_b32 v33, a86 offset:2720
	ds_write_b32 v32, a71 offset:2992
	ds_write_b32 v33, a87 offset:2992
	ds_write_b32 v32, a72 offset:4352
	ds_write_b32 v33, a88 offset:4352
	ds_write_b32 v32, a73 offset:4624
	ds_write_b32 v33, a89 offset:4624
	ds_write_b32 v32, a74 offset:4896
	ds_write_b32 v33, a90 offset:4896
	ds_write_b32 v32, a75 offset:5168
	ds_write_b32 v33, a91 offset:5168
	ds_write_b32 v32, a76 offset:6528
	ds_write_b32 v33, a92 offset:6528
	ds_write_b32 v32, a77 offset:6800
	ds_write_b32 v33, a93 offset:6800
	ds_write_b32 v32, a78 offset:7072
	ds_write_b32 v33, a94 offset:7072
	ds_write_b32 v32, a79 offset:7344
	ds_write_b32 v33, a95 offset:7344
	ds_read_b128 v[124:127], v48
	ds_read_b128 v[128:131], v48 offset:16
	ds_read_b128 v[132:135], v48 offset:2176
	ds_read_b128 v[136:139], v48 offset:2192
	ds_read_b128 v[140:143], v48 offset:4352
	ds_read_b128 v[144:147], v48 offset:4368
	ds_read_b128 v[148:151], v48 offset:6528
	ds_read_b128 v[152:155], v48 offset:6544
	ds_read_b128 v[0:3], v185
	ds_read_b128 v[4:7], v185 offset:16
	ds_read_b128 v[8:11], v185 offset:2176
	ds_read_b128 v[14:17], v185 offset:2192
	ds_read_b128 v[18:21], v185 offset:4352
	ds_read_b128 v[22:25], v185 offset:4368
	ds_read_b128 v[26:29], v185 offset:6528
	ds_read_b128 v[50:53], v185 offset:6544
	s_movk_i32 s49, 6
	s_branch .Lep_compute

.Lep_nt6:
	ds_write_b32 v32, a32
	ds_write_b32 v33, a48
	ds_write_b32 v32, a33 offset:272
	ds_write_b32 v33, a49 offset:272
	ds_write_b32 v32, a34 offset:544
	ds_write_b32 v33, a50 offset:544
	ds_write_b32 v32, a35 offset:816
	ds_write_b32 v33, a51 offset:816
	ds_write_b32 v32, a36 offset:2176
	ds_write_b32 v33, a52 offset:2176
	ds_write_b32 v32, a37 offset:2448
	ds_write_b32 v33, a53 offset:2448
	ds_write_b32 v32, a38 offset:2720
	ds_write_b32 v33, a54 offset:2720
	ds_write_b32 v32, a39 offset:2992
	ds_write_b32 v33, a55 offset:2992
	ds_write_b32 v32, a40 offset:4352
	ds_write_b32 v33, a56 offset:4352
	ds_write_b32 v32, a41 offset:4624
	ds_write_b32 v33, a57 offset:4624
	ds_write_b32 v32, a42 offset:4896
	ds_write_b32 v33, a58 offset:4896
	ds_write_b32 v32, a43 offset:5168
	ds_write_b32 v33, a59 offset:5168
	ds_write_b32 v32, a44 offset:6528
	ds_write_b32 v33, a60 offset:6528
	ds_write_b32 v32, a45 offset:6800
	ds_write_b32 v33, a61 offset:6800
	ds_write_b32 v32, a46 offset:7072
	ds_write_b32 v33, a62 offset:7072
	ds_write_b32 v32, a47 offset:7344
	ds_write_b32 v33, a63 offset:7344
	ds_read_b128 v[124:127], v48
	ds_read_b128 v[128:131], v48 offset:16
	ds_read_b128 v[132:135], v48 offset:2176
	ds_read_b128 v[136:139], v48 offset:2192
	ds_read_b128 v[140:143], v48 offset:4352
	ds_read_b128 v[144:147], v48 offset:4368
	ds_read_b128 v[148:151], v48 offset:6528
	ds_read_b128 v[152:155], v48 offset:6544
	ds_read_b128 v[0:3], v185
	ds_read_b128 v[4:7], v185 offset:16
	ds_read_b128 v[8:11], v185 offset:2176
	ds_read_b128 v[14:17], v185 offset:2192
	ds_read_b128 v[18:21], v185 offset:4352
	ds_read_b128 v[22:25], v185 offset:4368
	ds_read_b128 v[26:29], v185 offset:6528
	ds_read_b128 v[50:53], v185 offset:6544
	s_movk_i32 s49, 7
	s_branch .Lep_compute

.Lep_nt7:
	ds_write_b32 v32, a16
	ds_write_b32 v33, a0
	ds_write_b32 v32, a17 offset:272
	ds_write_b32 v33, a1 offset:272
	ds_write_b32 v32, a18 offset:544
	ds_write_b32 v33, a2 offset:544
	ds_write_b32 v32, a19 offset:816
	ds_write_b32 v33, a3 offset:816
	ds_write_b32 v32, a20 offset:2176
	ds_write_b32 v33, a4 offset:2176
	ds_write_b32 v32, a21 offset:2448
	ds_write_b32 v33, a5 offset:2448
	ds_write_b32 v32, a22 offset:2720
	ds_write_b32 v33, a6 offset:2720
	ds_write_b32 v32, a23 offset:2992
	ds_write_b32 v33, a7 offset:2992
	ds_write_b32 v32, a24 offset:4352
	ds_write_b32 v33, a8 offset:4352
	ds_write_b32 v32, a25 offset:4624
	ds_write_b32 v33, a9 offset:4624
	ds_write_b32 v32, a26 offset:4896
	ds_write_b32 v33, a10 offset:4896
	ds_write_b32 v32, a27 offset:5168
	ds_write_b32 v33, a11 offset:5168
	ds_write_b32 v32, a28 offset:6528
	ds_write_b32 v33, a12 offset:6528
	ds_write_b32 v32, a29 offset:6800
	ds_write_b32 v33, a13 offset:6800
	ds_write_b32 v32, a30 offset:7072
	ds_write_b32 v33, a14 offset:7072
	ds_write_b32 v32, a31 offset:7344
	ds_write_b32 v33, a15 offset:7344
	ds_read_b128 v[124:127], v48
	ds_read_b128 v[128:131], v48 offset:16
	ds_read_b128 v[132:135], v48 offset:2176
	ds_read_b128 v[136:139], v48 offset:2192
	ds_read_b128 v[140:143], v48 offset:4352
	ds_read_b128 v[144:147], v48 offset:4368
	ds_read_b128 v[148:151], v48 offset:6528
	ds_read_b128 v[152:155], v48 offset:6544
	ds_read_b128 v[0:3], v185
	ds_read_b128 v[4:7], v185 offset:16
	ds_read_b128 v[8:11], v185 offset:2176
	ds_read_b128 v[14:17], v185 offset:2192
	ds_read_b128 v[18:21], v185 offset:4352
	ds_read_b128 v[22:25], v185 offset:4368
	ds_read_b128 v[26:29], v185 offset:6528
	ds_read_b128 v[50:53], v185 offset:6544
	s_movk_i32 s49, 8
	s_branch .Lep_compute
.Lep_compute:
	s_cmp_eq_u32 s51, 2
	s_cbranch_scc1 .Lep_sigm
	s_cmp_eq_u32 s51, 1
	s_cbranch_scc1 .Lep_silu
	s_cmp_eq_u32 s51, 3
	s_cbranch_scc1 .Lep_rope
	s_cmp_eq_u32 s51, 4
	s_cbranch_scc1 .Lep_ropec
	s_cmp_eq_u32 s51, 5
	s_cbranch_scc1 .Lep_plainc
	s_waitcnt lgkmcnt(6)
	v_pk_mul_f32 v[156:157], v[124:125], s[10:11]
	v_pk_mul_f32 v[158:159], v[126:127], s[10:11]
	v_pk_mul_f32 v[160:161], v[128:129], s[10:11]
	v_pk_mul_f32 v[162:163], v[130:131], s[10:11]
	v_cvt_pk_f16_f32 v174, v156, v157
	v_cvt_pk_f16_f32 v175, v158, v159
	v_cvt_pk_f16_f32 v176, v160, v161
	v_cvt_pk_f16_f32 v177, v162, v163
	global_store_dwordx4 v[172:173], v[174:177], off nt
	v_lshl_add_u64 v[172:173], v[172:173], 0, s[12:13]
	s_waitcnt lgkmcnt(4)
	v_pk_mul_f32 v[164:165], v[132:133], s[10:11]
	v_pk_mul_f32 v[166:167], v[134:135], s[10:11]
	v_pk_mul_f32 v[168:169], v[136:137], s[10:11]
	v_pk_mul_f32 v[170:171], v[138:139], s[10:11]
	v_cvt_pk_f16_f32 v174, v164, v165
	v_cvt_pk_f16_f32 v175, v166, v167
	v_cvt_pk_f16_f32 v176, v168, v169
	v_cvt_pk_f16_f32 v177, v170, v171
	global_store_dwordx4 v[172:173], v[174:177], off nt
	v_lshl_add_u64 v[172:173], v[172:173], 0, s[12:13]
	s_waitcnt lgkmcnt(2)
	v_pk_mul_f32 v[156:157], v[140:141], s[10:11]
	v_pk_mul_f32 v[158:159], v[142:143], s[10:11]
	v_pk_mul_f32 v[160:161], v[144:145], s[10:11]
	v_pk_mul_f32 v[162:163], v[146:147], s[10:11]
	v_cvt_pk_f16_f32 v174, v156, v157
	v_cvt_pk_f16_f32 v175, v158, v159
	v_cvt_pk_f16_f32 v176, v160, v161
	v_cvt_pk_f16_f32 v177, v162, v163
	global_store_dwordx4 v[172:173], v[174:177], off nt
	v_lshl_add_u64 v[172:173], v[172:173], 0, s[12:13]
	s_waitcnt lgkmcnt(0)
	v_pk_mul_f32 v[164:165], v[148:149], s[10:11]
	v_pk_mul_f32 v[166:167], v[150:151], s[10:11]
	v_pk_mul_f32 v[168:169], v[152:153], s[10:11]
	v_pk_mul_f32 v[170:171], v[154:155], s[10:11]
	v_cvt_pk_f16_f32 v174, v164, v165
	v_cvt_pk_f16_f32 v175, v166, v167
	v_cvt_pk_f16_f32 v176, v168, v169
	v_cvt_pk_f16_f32 v177, v170, v171
	global_store_dwordx4 v[172:173], v[174:177], off nt
	v_lshl_add_u64 v[172:173], v[172:173], 0, s[12:13]
	s_branch .Lep_ret
.Lep_silu:
	s_waitcnt lgkmcnt(6)
	v_pk_mul_f32 v[156:157], v[124:125], s[16:17]
	v_pk_mul_f32 v[158:159], v[126:127], s[16:17]
	v_pk_mul_f32 v[160:161], v[128:129], s[16:17]
	v_pk_mul_f32 v[162:163], v[130:131], s[16:17]
	v_exp_f32_e32 v156, v156
	v_exp_f32_e32 v157, v157
	v_exp_f32_e32 v158, v158
	v_exp_f32_e32 v159, v159
	v_pk_add_f32 v[156:157], v[156:157], 1.0 op_sel_hi:[1,0]
	v_exp_f32_e32 v160, v160
	v_exp_f32_e32 v161, v161
	v_pk_add_f32 v[158:159], v[158:159], 1.0 op_sel_hi:[1,0]
	v_exp_f32_e32 v162, v162
	v_exp_f32_e32 v163, v163
	v_rcp_f32_e32 v156, v156
	v_rcp_f32_e32 v157, v157
	v_pk_add_f32 v[160:161], v[160:161], 1.0 op_sel_hi:[1,0]
	v_rcp_f32_e32 v158, v158
	v_rcp_f32_e32 v159, v159
	v_pk_add_f32 v[162:163], v[162:163], 1.0 op_sel_hi:[1,0]
	v_rcp_f32_e32 v160, v160
	v_rcp_f32_e32 v161, v161
	v_pk_mul_f32 v[156:157], v[156:157], v[124:125]
	v_rcp_f32_e32 v162, v162
	v_pk_mul_f32 v[158:159], v[158:159], v[126:127]
	v_rcp_f32_e32 v163, v163
	v_pk_mul_f32 v[160:161], v[160:161], v[128:129]
	v_pk_mul_f32 v[162:163], v[162:163], v[130:131]
	v_cvt_pk_f16_f32 v174, v156, v157
	v_cvt_pk_f16_f32 v175, v158, v159
	v_cvt_pk_f16_f32 v176, v160, v161
	v_cvt_pk_f16_f32 v177, v162, v163
	global_store_dwordx4 v[172:173], v[174:177], off nt
	v_lshl_add_u64 v[172:173], v[172:173], 0, s[12:13]
	s_waitcnt lgkmcnt(4)
	v_pk_mul_f32 v[164:165], v[132:133], s[16:17]
	v_pk_mul_f32 v[166:167], v[134:135], s[16:17]
	v_pk_mul_f32 v[168:169], v[136:137], s[16:17]
	v_pk_mul_f32 v[170:171], v[138:139], s[16:17]
	v_exp_f32_e32 v164, v164
	v_exp_f32_e32 v165, v165
	v_exp_f32_e32 v166, v166
	v_exp_f32_e32 v167, v167
	v_pk_add_f32 v[164:165], v[164:165], 1.0 op_sel_hi:[1,0]
	v_exp_f32_e32 v168, v168
	v_exp_f32_e32 v169, v169
	v_pk_add_f32 v[166:167], v[166:167], 1.0 op_sel_hi:[1,0]
	v_exp_f32_e32 v170, v170
	v_exp_f32_e32 v171, v171
	v_rcp_f32_e32 v164, v164
	v_rcp_f32_e32 v165, v165
	v_pk_add_f32 v[168:169], v[168:169], 1.0 op_sel_hi:[1,0]
	v_rcp_f32_e32 v166, v166
	v_rcp_f32_e32 v167, v167
	v_pk_add_f32 v[170:171], v[170:171], 1.0 op_sel_hi:[1,0]
	v_rcp_f32_e32 v168, v168
	v_rcp_f32_e32 v169, v169
	v_pk_mul_f32 v[164:165], v[164:165], v[132:133]
	v_rcp_f32_e32 v170, v170
	v_pk_mul_f32 v[166:167], v[166:167], v[134:135]
	v_rcp_f32_e32 v171, v171
	v_pk_mul_f32 v[168:169], v[168:169], v[136:137]
	v_pk_mul_f32 v[170:171], v[170:171], v[138:139]
	v_cvt_pk_f16_f32 v174, v164, v165
	v_cvt_pk_f16_f32 v175, v166, v167
	v_cvt_pk_f16_f32 v176, v168, v169
	v_cvt_pk_f16_f32 v177, v170, v171
	global_store_dwordx4 v[172:173], v[174:177], off nt
	v_lshl_add_u64 v[172:173], v[172:173], 0, s[12:13]
	s_waitcnt lgkmcnt(2)
	v_pk_mul_f32 v[156:157], v[140:141], s[16:17]
	v_pk_mul_f32 v[158:159], v[142:143], s[16:17]
	v_pk_mul_f32 v[160:161], v[144:145], s[16:17]
	v_pk_mul_f32 v[162:163], v[146:147], s[16:17]
	v_exp_f32_e32 v156, v156
	v_exp_f32_e32 v157, v157
	v_exp_f32_e32 v158, v158
	v_exp_f32_e32 v159, v159
	v_pk_add_f32 v[156:157], v[156:157], 1.0 op_sel_hi:[1,0]
	v_exp_f32_e32 v160, v160
	v_exp_f32_e32 v161, v161
	v_pk_add_f32 v[158:159], v[158:159], 1.0 op_sel_hi:[1,0]
	v_exp_f32_e32 v162, v162
	v_exp_f32_e32 v163, v163
	v_rcp_f32_e32 v156, v156
	v_rcp_f32_e32 v157, v157
	v_pk_add_f32 v[160:161], v[160:161], 1.0 op_sel_hi:[1,0]
	v_rcp_f32_e32 v158, v158
	v_rcp_f32_e32 v159, v159
	v_pk_add_f32 v[162:163], v[162:163], 1.0 op_sel_hi:[1,0]
	v_rcp_f32_e32 v160, v160
	v_rcp_f32_e32 v161, v161
	v_pk_mul_f32 v[156:157], v[156:157], v[140:141]
	v_rcp_f32_e32 v162, v162
	v_pk_mul_f32 v[158:159], v[158:159], v[142:143]
	v_rcp_f32_e32 v163, v163
	v_pk_mul_f32 v[160:161], v[160:161], v[144:145]
	v_pk_mul_f32 v[162:163], v[162:163], v[146:147]
	v_cvt_pk_f16_f32 v174, v156, v157
	v_cvt_pk_f16_f32 v175, v158, v159
	v_cvt_pk_f16_f32 v176, v160, v161
	v_cvt_pk_f16_f32 v177, v162, v163
	global_store_dwordx4 v[172:173], v[174:177], off nt
	v_lshl_add_u64 v[172:173], v[172:173], 0, s[12:13]
	s_waitcnt lgkmcnt(0)
	v_pk_mul_f32 v[164:165], v[148:149], s[16:17]
	v_pk_mul_f32 v[166:167], v[150:151], s[16:17]
	v_pk_mul_f32 v[168:169], v[152:153], s[16:17]
	v_pk_mul_f32 v[170:171], v[154:155], s[16:17]
	v_exp_f32_e32 v164, v164
	v_exp_f32_e32 v165, v165
	v_exp_f32_e32 v166, v166
	v_exp_f32_e32 v167, v167
	v_pk_add_f32 v[164:165], v[164:165], 1.0 op_sel_hi:[1,0]
	v_exp_f32_e32 v168, v168
	v_exp_f32_e32 v169, v169
	v_pk_add_f32 v[166:167], v[166:167], 1.0 op_sel_hi:[1,0]
	v_exp_f32_e32 v170, v170
	v_exp_f32_e32 v171, v171
	v_rcp_f32_e32 v164, v164
	v_rcp_f32_e32 v165, v165
	v_pk_add_f32 v[168:169], v[168:169], 1.0 op_sel_hi:[1,0]
	v_rcp_f32_e32 v166, v166
	v_rcp_f32_e32 v167, v167
	v_pk_add_f32 v[170:171], v[170:171], 1.0 op_sel_hi:[1,0]
	v_rcp_f32_e32 v168, v168
	v_rcp_f32_e32 v169, v169
	v_pk_mul_f32 v[164:165], v[164:165], v[148:149]
	v_rcp_f32_e32 v170, v170
	v_pk_mul_f32 v[166:167], v[166:167], v[150:151]
	v_rcp_f32_e32 v171, v171
	v_pk_mul_f32 v[168:169], v[168:169], v[152:153]
	v_pk_mul_f32 v[170:171], v[170:171], v[154:155]
	v_cvt_pk_f16_f32 v174, v164, v165
	v_cvt_pk_f16_f32 v175, v166, v167
	v_cvt_pk_f16_f32 v176, v168, v169
	v_cvt_pk_f16_f32 v177, v170, v171
	global_store_dwordx4 v[172:173], v[174:177], off nt
	v_lshl_add_u64 v[172:173], v[172:173], 0, s[12:13]
	s_branch .Lep_ret
.Lep_sigm:
	s_waitcnt lgkmcnt(6)
	v_pk_mul_f32 v[156:157], v[124:125], s[16:17]
	v_pk_mul_f32 v[158:159], v[126:127], s[16:17]
	v_pk_mul_f32 v[160:161], v[128:129], s[16:17]
	v_pk_mul_f32 v[162:163], v[130:131], s[16:17]
	v_exp_f32_e32 v156, v156
	v_exp_f32_e32 v157, v157
	v_exp_f32_e32 v158, v158
	v_exp_f32_e32 v159, v159
	v_pk_add_f32 v[156:157], v[156:157], 1.0 op_sel_hi:[1,0]
	v_exp_f32_e32 v160, v160
	v_exp_f32_e32 v161, v161
	v_pk_add_f32 v[158:159], v[158:159], 1.0 op_sel_hi:[1,0]
	v_exp_f32_e32 v162, v162
	v_exp_f32_e32 v163, v163
	v_rcp_f32_e32 v156, v156
	v_rcp_f32_e32 v157, v157
	v_pk_add_f32 v[160:161], v[160:161], 1.0 op_sel_hi:[1,0]
	v_rcp_f32_e32 v158, v158
	v_rcp_f32_e32 v159, v159
	v_pk_add_f32 v[162:163], v[162:163], 1.0 op_sel_hi:[1,0]
	v_rcp_f32_e32 v160, v160
	v_rcp_f32_e32 v161, v161
	v_rcp_f32_e32 v162, v162
	v_rcp_f32_e32 v163, v163
	v_cvt_pk_f16_f32 v174, v156, v157
	v_cvt_pk_f16_f32 v175, v158, v159
	v_cvt_pk_f16_f32 v176, v160, v161
	v_cvt_pk_f16_f32 v177, v162, v163
	global_store_dwordx4 v[172:173], v[174:177], off nt
	v_lshl_add_u64 v[172:173], v[172:173], 0, s[12:13]
	s_waitcnt lgkmcnt(4)
	v_pk_mul_f32 v[164:165], v[132:133], s[16:17]
	v_pk_mul_f32 v[166:167], v[134:135], s[16:17]
	v_pk_mul_f32 v[168:169], v[136:137], s[16:17]
	v_pk_mul_f32 v[170:171], v[138:139], s[16:17]
	v_exp_f32_e32 v164, v164
	v_exp_f32_e32 v165, v165
	v_exp_f32_e32 v166, v166
	v_exp_f32_e32 v167, v167
	v_pk_add_f32 v[164:165], v[164:165], 1.0 op_sel_hi:[1,0]
	v_exp_f32_e32 v168, v168
	v_exp_f32_e32 v169, v169
	v_pk_add_f32 v[166:167], v[166:167], 1.0 op_sel_hi:[1,0]
	v_exp_f32_e32 v170, v170
	v_exp_f32_e32 v171, v171
	v_rcp_f32_e32 v164, v164
	v_rcp_f32_e32 v165, v165
	v_pk_add_f32 v[168:169], v[168:169], 1.0 op_sel_hi:[1,0]
	v_rcp_f32_e32 v166, v166
	v_rcp_f32_e32 v167, v167
	v_pk_add_f32 v[170:171], v[170:171], 1.0 op_sel_hi:[1,0]
	v_rcp_f32_e32 v168, v168
	v_rcp_f32_e32 v169, v169
	v_rcp_f32_e32 v170, v170
	v_rcp_f32_e32 v171, v171
	v_cvt_pk_f16_f32 v174, v164, v165
	v_cvt_pk_f16_f32 v175, v166, v167
	v_cvt_pk_f16_f32 v176, v168, v169
	v_cvt_pk_f16_f32 v177, v170, v171
	global_store_dwordx4 v[172:173], v[174:177], off nt
	v_lshl_add_u64 v[172:173], v[172:173], 0, s[12:13]
	s_waitcnt lgkmcnt(2)
	v_pk_mul_f32 v[156:157], v[140:141], s[16:17]
	v_pk_mul_f32 v[158:159], v[142:143], s[16:17]
	v_pk_mul_f32 v[160:161], v[144:145], s[16:17]
	v_pk_mul_f32 v[162:163], v[146:147], s[16:17]
	v_exp_f32_e32 v156, v156
	v_exp_f32_e32 v157, v157
	v_exp_f32_e32 v158, v158
	v_exp_f32_e32 v159, v159
	v_pk_add_f32 v[156:157], v[156:157], 1.0 op_sel_hi:[1,0]
	v_exp_f32_e32 v160, v160
	v_exp_f32_e32 v161, v161
	v_pk_add_f32 v[158:159], v[158:159], 1.0 op_sel_hi:[1,0]
	v_exp_f32_e32 v162, v162
	v_exp_f32_e32 v163, v163
	v_rcp_f32_e32 v156, v156
	v_rcp_f32_e32 v157, v157
	v_pk_add_f32 v[160:161], v[160:161], 1.0 op_sel_hi:[1,0]
	v_rcp_f32_e32 v158, v158
	v_rcp_f32_e32 v159, v159
	v_pk_add_f32 v[162:163], v[162:163], 1.0 op_sel_hi:[1,0]
	v_rcp_f32_e32 v160, v160
	v_rcp_f32_e32 v161, v161
	v_rcp_f32_e32 v162, v162
	v_rcp_f32_e32 v163, v163
	v_cvt_pk_f16_f32 v174, v156, v157
	v_cvt_pk_f16_f32 v175, v158, v159
	v_cvt_pk_f16_f32 v176, v160, v161
	v_cvt_pk_f16_f32 v177, v162, v163
	global_store_dwordx4 v[172:173], v[174:177], off nt
	v_lshl_add_u64 v[172:173], v[172:173], 0, s[12:13]
	s_waitcnt lgkmcnt(0)
	v_pk_mul_f32 v[164:165], v[148:149], s[16:17]
	v_pk_mul_f32 v[166:167], v[150:151], s[16:17]
	v_pk_mul_f32 v[168:169], v[152:153], s[16:17]
	v_pk_mul_f32 v[170:171], v[154:155], s[16:17]
	v_exp_f32_e32 v164, v164
	v_exp_f32_e32 v165, v165
	v_exp_f32_e32 v166, v166
	v_exp_f32_e32 v167, v167
	v_pk_add_f32 v[164:165], v[164:165], 1.0 op_sel_hi:[1,0]
	v_exp_f32_e32 v168, v168
	v_exp_f32_e32 v169, v169
	v_pk_add_f32 v[166:167], v[166:167], 1.0 op_sel_hi:[1,0]
	v_exp_f32_e32 v170, v170
	v_exp_f32_e32 v171, v171
	v_rcp_f32_e32 v164, v164
	v_rcp_f32_e32 v165, v165
	v_pk_add_f32 v[168:169], v[168:169], 1.0 op_sel_hi:[1,0]
	v_rcp_f32_e32 v166, v166
	v_rcp_f32_e32 v167, v167
	v_pk_add_f32 v[170:171], v[170:171], 1.0 op_sel_hi:[1,0]
	v_rcp_f32_e32 v168, v168
	v_rcp_f32_e32 v169, v169
	v_rcp_f32_e32 v170, v170
	v_rcp_f32_e32 v171, v171
	v_cvt_pk_f16_f32 v174, v164, v165
	v_cvt_pk_f16_f32 v175, v166, v167
	v_cvt_pk_f16_f32 v176, v168, v169
	v_cvt_pk_f16_f32 v177, v170, v171
	global_store_dwordx4 v[172:173], v[174:177], off nt
	v_lshl_add_u64 v[172:173], v[172:173], 0, s[12:13]
	s_branch .Lep_ret
.Lep_rope:
	s_waitcnt lgkmcnt(6)
	s_waitcnt vmcnt(12)
	s_mov_b64 exec, s[36:37]
	v_pk_mul_f32 v[0:1], v[0:1], -1.0 op_sel_hi:[1,0]
	v_pk_mul_f32 v[2:3], v[2:3], -1.0 op_sel_hi:[1,0]
	v_pk_mul_f32 v[4:5], v[4:5], -1.0 op_sel_hi:[1,0]
	v_pk_mul_f32 v[6:7], v[6:7], -1.0 op_sel_hi:[1,0]
	s_mov_b64 exec, s[34:35]
	v_mul_f32_e32 v0, v0, v187
	v_mul_f32_e32 v1, v1, v189
	v_mul_f32_e32 v2, v2, v191
	v_mul_f32_e32 v3, v3, v193
	v_mul_f32_e32 v4, v4, v195
	v_mul_f32_e32 v5, v5, v197
	v_mul_f32_e32 v6, v6, v199
	v_mul_f32_e32 v7, v7, v201
	v_fma_f32 v124, v124, v186, v0
	v_fma_f32 v125, v125, v188, v1
	v_fma_f32 v126, v126, v190, v2
	v_fma_f32 v127, v127, v192, v3
	v_fma_f32 v128, v128, v194, v4
	v_fma_f32 v129, v129, v196, v5
	v_fma_f32 v130, v130, v198, v6
	v_fma_f32 v131, v131, v200, v7
	s_mov_b64 exec, -1
	v_pk_mul_f32 v[156:157], v[124:125], s[10:11]
	v_pk_mul_f32 v[158:159], v[126:127], s[10:11]
	v_pk_mul_f32 v[160:161], v[128:129], s[10:11]
	v_pk_mul_f32 v[162:163], v[130:131], s[10:11]
	v_cvt_pk_f16_f32 v174, v156, v157
	v_cvt_pk_f16_f32 v175, v158, v159
	v_cvt_pk_f16_f32 v176, v160, v161
	v_cvt_pk_f16_f32 v177, v162, v163
	global_store_dwordx4 v[172:173], v[174:177], off nt
	v_lshl_add_u64 v[172:173], v[172:173], 0, s[12:13]
	s_waitcnt lgkmcnt(4)
	s_waitcnt vmcnt(9)
	s_mov_b64 exec, s[36:37]
	v_pk_mul_f32 v[8:9], v[8:9], -1.0 op_sel_hi:[1,0]
	v_pk_mul_f32 v[10:11], v[10:11], -1.0 op_sel_hi:[1,0]
	v_pk_mul_f32 v[14:15], v[14:15], -1.0 op_sel_hi:[1,0]
	v_pk_mul_f32 v[16:17], v[16:17], -1.0 op_sel_hi:[1,0]
	s_mov_b64 exec, s[34:35]
	v_mul_f32_e32 v8, v8, v203
	v_mul_f32_e32 v9, v9, v205
	v_mul_f32_e32 v10, v10, v207
	v_mul_f32_e32 v11, v11, v209
	v_mul_f32_e32 v14, v14, v211
	v_mul_f32_e32 v15, v15, v213
	v_mul_f32_e32 v16, v16, v215
	v_mul_f32_e32 v17, v17, v217
	v_fma_f32 v132, v132, v202, v8
	v_fma_f32 v133, v133, v204, v9
	v_fma_f32 v134, v134, v206, v10
	v_fma_f32 v135, v135, v208, v11
	v_fma_f32 v136, v136, v210, v14
	v_fma_f32 v137, v137, v212, v15
	v_fma_f32 v138, v138, v214, v16
	v_fma_f32 v139, v139, v216, v17
	s_mov_b64 exec, -1
	v_pk_mul_f32 v[164:165], v[132:133], s[10:11]
	v_pk_mul_f32 v[166:167], v[134:135], s[10:11]
	v_pk_mul_f32 v[168:169], v[136:137], s[10:11]
	v_pk_mul_f32 v[170:171], v[138:139], s[10:11]
	v_cvt_pk_f16_f32 v174, v164, v165
	v_cvt_pk_f16_f32 v175, v166, v167
	v_cvt_pk_f16_f32 v176, v168, v169
	v_cvt_pk_f16_f32 v177, v170, v171
	global_store_dwordx4 v[172:173], v[174:177], off nt
	v_lshl_add_u64 v[172:173], v[172:173], 0, s[12:13]
	s_waitcnt lgkmcnt(2)
	s_waitcnt vmcnt(6)
	s_mov_b64 exec, s[36:37]
	v_pk_mul_f32 v[18:19], v[18:19], -1.0 op_sel_hi:[1,0]
	v_pk_mul_f32 v[20:21], v[20:21], -1.0 op_sel_hi:[1,0]
	v_pk_mul_f32 v[22:23], v[22:23], -1.0 op_sel_hi:[1,0]
	v_pk_mul_f32 v[24:25], v[24:25], -1.0 op_sel_hi:[1,0]
	s_mov_b64 exec, s[34:35]
	v_mul_f32_e32 v18, v18, v219
	v_mul_f32_e32 v19, v19, v221
	v_mul_f32_e32 v20, v20, v223
	v_mul_f32_e32 v21, v21, v225
	v_mul_f32_e32 v22, v22, v227
	v_mul_f32_e32 v23, v23, v229
	v_mul_f32_e32 v24, v24, v231
	v_mul_f32_e32 v25, v25, v233
	v_fma_f32 v140, v140, v218, v18
	v_fma_f32 v141, v141, v220, v19
	v_fma_f32 v142, v142, v222, v20
	v_fma_f32 v143, v143, v224, v21
	v_fma_f32 v144, v144, v226, v22
	v_fma_f32 v145, v145, v228, v23
	v_fma_f32 v146, v146, v230, v24
	v_fma_f32 v147, v147, v232, v25
	s_mov_b64 exec, -1
	v_pk_mul_f32 v[156:157], v[140:141], s[10:11]
	v_pk_mul_f32 v[158:159], v[142:143], s[10:11]
	v_pk_mul_f32 v[160:161], v[144:145], s[10:11]
	v_pk_mul_f32 v[162:163], v[146:147], s[10:11]
	v_cvt_pk_f16_f32 v174, v156, v157
	v_cvt_pk_f16_f32 v175, v158, v159
	v_cvt_pk_f16_f32 v176, v160, v161
	v_cvt_pk_f16_f32 v177, v162, v163
	global_store_dwordx4 v[172:173], v[174:177], off nt
	v_lshl_add_u64 v[172:173], v[172:173], 0, s[12:13]
	s_waitcnt lgkmcnt(0)
	s_waitcnt vmcnt(3)
	s_mov_b64 exec, s[36:37]
	v_pk_mul_f32 v[26:27], v[26:27], -1.0 op_sel_hi:[1,0]
	v_pk_mul_f32 v[28:29], v[28:29], -1.0 op_sel_hi:[1,0]
	v_pk_mul_f32 v[50:51], v[50:51], -1.0 op_sel_hi:[1,0]
	v_pk_mul_f32 v[52:53], v[52:53], -1.0 op_sel_hi:[1,0]
	s_mov_b64 exec, s[34:35]
	v_mul_f32_e32 v26, v26, v235
	v_mul_f32_e32 v27, v27, v237
	v_mul_f32_e32 v28, v28, v239
	v_mul_f32_e32 v29, v29, v241
	v_mul_f32_e32 v50, v50, v243
	v_mul_f32_e32 v51, v51, v245
	v_mul_f32_e32 v52, v52, v247
	v_mul_f32_e32 v53, v53, v249
	v_fma_f32 v148, v148, v234, v26
	v_fma_f32 v149, v149, v236, v27
	v_fma_f32 v150, v150, v238, v28
	v_fma_f32 v151, v151, v240, v29
	v_fma_f32 v152, v152, v242, v50
	v_fma_f32 v153, v153, v244, v51
	v_fma_f32 v154, v154, v246, v52
	v_fma_f32 v155, v155, v248, v53
	s_mov_b64 exec, -1
	v_pk_mul_f32 v[164:165], v[148:149], s[10:11]
	v_pk_mul_f32 v[166:167], v[150:151], s[10:11]
	v_pk_mul_f32 v[168:169], v[152:153], s[10:11]
	v_pk_mul_f32 v[170:171], v[154:155], s[10:11]
	v_cvt_pk_f16_f32 v174, v164, v165
	v_cvt_pk_f16_f32 v175, v166, v167
	v_cvt_pk_f16_f32 v176, v168, v169
	v_cvt_pk_f16_f32 v177, v170, v171
	global_store_dwordx4 v[172:173], v[174:177], off nt
	v_lshl_add_u64 v[172:173], v[172:173], 0, s[12:13]
	s_branch .Lep_ret
.Lep_ropec:
	s_waitcnt lgkmcnt(6)
	s_waitcnt vmcnt(12)
	s_mov_b64 exec, s[36:37]
	v_pk_mul_f32 v[0:1], v[0:1], -1.0 op_sel_hi:[1,0]
	v_pk_mul_f32 v[2:3], v[2:3], -1.0 op_sel_hi:[1,0]
	v_pk_mul_f32 v[4:5], v[4:5], -1.0 op_sel_hi:[1,0]
	v_pk_mul_f32 v[6:7], v[6:7], -1.0 op_sel_hi:[1,0]
	s_mov_b64 exec, s[34:35]
	v_mul_f32_e32 v0, v0, v187
	v_mul_f32_e32 v1, v1, v189
	v_mul_f32_e32 v2, v2, v191
	v_mul_f32_e32 v3, v3, v193
	v_mul_f32_e32 v4, v4, v195
	v_mul_f32_e32 v5, v5, v197
	v_mul_f32_e32 v6, v6, v199
	v_mul_f32_e32 v7, v7, v201
	v_fma_f32 v124, v124, v186, v0
	v_fma_f32 v125, v125, v188, v1
	v_fma_f32 v126, v126, v190, v2
	v_fma_f32 v127, v127, v192, v3
	v_fma_f32 v128, v128, v194, v4
	v_fma_f32 v129, v129, v196, v5
	v_fma_f32 v130, v130, v198, v6
	v_fma_f32 v131, v131, v200, v7
	s_mov_b64 exec, -1
	v_pk_mul_f32 v[156:157], v[124:125], s[10:11]
	v_pk_mul_f32 v[158:159], v[126:127], s[10:11]
	v_pk_mul_f32 v[160:161], v[128:129], s[10:11]
	v_pk_mul_f32 v[162:163], v[130:131], s[10:11]
	v_cvt_pk_f16_f32 v174, v156, v157
	v_cvt_pk_f16_f32 v175, v158, v159
	v_cvt_pk_f16_f32 v176, v160, v161
	v_cvt_pk_f16_f32 v177, v162, v163
	global_store_dwordx4 v[172:173], v[174:177], off nt
	global_store_dwordx4 v[182:183], v[174:177], off
	v_lshl_add_u64 v[182:183], v[182:183], 0, s[8:9]
	v_lshl_add_u64 v[172:173], v[172:173], 0, s[12:13]
	s_waitcnt lgkmcnt(4)
	s_waitcnt vmcnt(10)
	s_mov_b64 exec, s[36:37]
	v_pk_mul_f32 v[8:9], v[8:9], -1.0 op_sel_hi:[1,0]
	v_pk_mul_f32 v[10:11], v[10:11], -1.0 op_sel_hi:[1,0]
	v_pk_mul_f32 v[14:15], v[14:15], -1.0 op_sel_hi:[1,0]
	v_pk_mul_f32 v[16:17], v[16:17], -1.0 op_sel_hi:[1,0]
	s_mov_b64 exec, s[34:35]
	v_mul_f32_e32 v8, v8, v203
	v_mul_f32_e32 v9, v9, v205
	v_mul_f32_e32 v10, v10, v207
	v_mul_f32_e32 v11, v11, v209
	v_mul_f32_e32 v14, v14, v211
	v_mul_f32_e32 v15, v15, v213
	v_mul_f32_e32 v16, v16, v215
	v_mul_f32_e32 v17, v17, v217
	v_fma_f32 v132, v132, v202, v8
	v_fma_f32 v133, v133, v204, v9
	v_fma_f32 v134, v134, v206, v10
	v_fma_f32 v135, v135, v208, v11
	v_fma_f32 v136, v136, v210, v14
	v_fma_f32 v137, v137, v212, v15
	v_fma_f32 v138, v138, v214, v16
	v_fma_f32 v139, v139, v216, v17
	s_mov_b64 exec, -1
	v_pk_mul_f32 v[164:165], v[132:133], s[10:11]
	v_pk_mul_f32 v[166:167], v[134:135], s[10:11]
	v_pk_mul_f32 v[168:169], v[136:137], s[10:11]
	v_pk_mul_f32 v[170:171], v[138:139], s[10:11]
	v_cvt_pk_f16_f32 v174, v164, v165
	v_cvt_pk_f16_f32 v175, v166, v167
	v_cvt_pk_f16_f32 v176, v168, v169
	v_cvt_pk_f16_f32 v177, v170, v171
	global_store_dwordx4 v[172:173], v[174:177], off nt
	global_store_dwordx4 v[182:183], v[174:177], off
	v_lshl_add_u64 v[182:183], v[182:183], 0, s[8:9]
	v_lshl_add_u64 v[172:173], v[172:173], 0, s[12:13]
	s_waitcnt lgkmcnt(2)
	s_waitcnt vmcnt(8)
	s_mov_b64 exec, s[36:37]
	v_pk_mul_f32 v[18:19], v[18:19], -1.0 op_sel_hi:[1,0]
	v_pk_mul_f32 v[20:21], v[20:21], -1.0 op_sel_hi:[1,0]
	v_pk_mul_f32 v[22:23], v[22:23], -1.0 op_sel_hi:[1,0]
	v_pk_mul_f32 v[24:25], v[24:25], -1.0 op_sel_hi:[1,0]
	s_mov_b64 exec, s[34:35]
	v_mul_f32_e32 v18, v18, v219
	v_mul_f32_e32 v19, v19, v221
	v_mul_f32_e32 v20, v20, v223
	v_mul_f32_e32 v21, v21, v225
	v_mul_f32_e32 v22, v22, v227
	v_mul_f32_e32 v23, v23, v229
	v_mul_f32_e32 v24, v24, v231
	v_mul_f32_e32 v25, v25, v233
	v_fma_f32 v140, v140, v218, v18
	v_fma_f32 v141, v141, v220, v19
	v_fma_f32 v142, v142, v222, v20
	v_fma_f32 v143, v143, v224, v21
	v_fma_f32 v144, v144, v226, v22
	v_fma_f32 v145, v145, v228, v23
	v_fma_f32 v146, v146, v230, v24
	v_fma_f32 v147, v147, v232, v25
	s_mov_b64 exec, -1
	v_pk_mul_f32 v[156:157], v[140:141], s[10:11]
	v_pk_mul_f32 v[158:159], v[142:143], s[10:11]
	v_pk_mul_f32 v[160:161], v[144:145], s[10:11]
	v_pk_mul_f32 v[162:163], v[146:147], s[10:11]
	v_cvt_pk_f16_f32 v174, v156, v157
	v_cvt_pk_f16_f32 v175, v158, v159
	v_cvt_pk_f16_f32 v176, v160, v161
	v_cvt_pk_f16_f32 v177, v162, v163
	global_store_dwordx4 v[172:173], v[174:177], off nt
	global_store_dwordx4 v[182:183], v[174:177], off
	v_lshl_add_u64 v[182:183], v[182:183], 0, s[8:9]
	v_lshl_add_u64 v[172:173], v[172:173], 0, s[12:13]
	s_waitcnt lgkmcnt(0)
	s_waitcnt vmcnt(6)
	s_mov_b64 exec, s[36:37]
	v_pk_mul_f32 v[26:27], v[26:27], -1.0 op_sel_hi:[1,0]
	v_pk_mul_f32 v[28:29], v[28:29], -1.0 op_sel_hi:[1,0]
	v_pk_mul_f32 v[50:51], v[50:51], -1.0 op_sel_hi:[1,0]
	v_pk_mul_f32 v[52:53], v[52:53], -1.0 op_sel_hi:[1,0]
	s_mov_b64 exec, s[34:35]
	v_mul_f32_e32 v26, v26, v235
	v_mul_f32_e32 v27, v27, v237
	v_mul_f32_e32 v28, v28, v239
	v_mul_f32_e32 v29, v29, v241
	v_mul_f32_e32 v50, v50, v243
	v_mul_f32_e32 v51, v51, v245
	v_mul_f32_e32 v52, v52, v247
	v_mul_f32_e32 v53, v53, v249
	v_fma_f32 v148, v148, v234, v26
	v_fma_f32 v149, v149, v236, v27
	v_fma_f32 v150, v150, v238, v28
	v_fma_f32 v151, v151, v240, v29
	v_fma_f32 v152, v152, v242, v50
	v_fma_f32 v153, v153, v244, v51
	v_fma_f32 v154, v154, v246, v52
	v_fma_f32 v155, v155, v248, v53
	s_mov_b64 exec, -1
	v_pk_mul_f32 v[164:165], v[148:149], s[10:11]
	v_pk_mul_f32 v[166:167], v[150:151], s[10:11]
	v_pk_mul_f32 v[168:169], v[152:153], s[10:11]
	v_pk_mul_f32 v[170:171], v[154:155], s[10:11]
	v_cvt_pk_f16_f32 v174, v164, v165
	v_cvt_pk_f16_f32 v175, v166, v167
	v_cvt_pk_f16_f32 v176, v168, v169
	v_cvt_pk_f16_f32 v177, v170, v171
	global_store_dwordx4 v[172:173], v[174:177], off nt
	global_store_dwordx4 v[182:183], v[174:177], off
	v_lshl_add_u64 v[182:183], v[182:183], 0, s[8:9]
	v_lshl_add_u64 v[172:173], v[172:173], 0, s[12:13]
	s_branch .Lep_ret
.Lep_plainc:
	s_waitcnt lgkmcnt(6)
	v_pk_mul_f32 v[156:157], v[124:125], s[10:11]
	v_pk_mul_f32 v[158:159], v[126:127], s[10:11]
	v_pk_mul_f32 v[160:161], v[128:129], s[10:11]
	v_pk_mul_f32 v[162:163], v[130:131], s[10:11]
	v_cvt_pk_f16_f32 v174, v156, v157
	v_cvt_pk_f16_f32 v175, v158, v159
	v_cvt_pk_f16_f32 v176, v160, v161
	v_cvt_pk_f16_f32 v177, v162, v163
	global_store_dwordx4 v[172:173], v[174:177], off nt
	global_store_dwordx4 v[182:183], v[174:177], off
	v_lshl_add_u64 v[182:183], v[182:183], 0, s[8:9]
	v_lshl_add_u64 v[172:173], v[172:173], 0, s[12:13]
	s_waitcnt lgkmcnt(4)
	v_pk_mul_f32 v[164:165], v[132:133], s[10:11]
	v_pk_mul_f32 v[166:167], v[134:135], s[10:11]
	v_pk_mul_f32 v[168:169], v[136:137], s[10:11]
	v_pk_mul_f32 v[170:171], v[138:139], s[10:11]
	v_cvt_pk_f16_f32 v174, v164, v165
	v_cvt_pk_f16_f32 v175, v166, v167
	v_cvt_pk_f16_f32 v176, v168, v169
	v_cvt_pk_f16_f32 v177, v170, v171
	global_store_dwordx4 v[172:173], v[174:177], off nt
	global_store_dwordx4 v[182:183], v[174:177], off
	v_lshl_add_u64 v[182:183], v[182:183], 0, s[8:9]
	v_lshl_add_u64 v[172:173], v[172:173], 0, s[12:13]
	s_waitcnt lgkmcnt(2)
	v_pk_mul_f32 v[156:157], v[140:141], s[10:11]
	v_pk_mul_f32 v[158:159], v[142:143], s[10:11]
	v_pk_mul_f32 v[160:161], v[144:145], s[10:11]
	v_pk_mul_f32 v[162:163], v[146:147], s[10:11]
	v_cvt_pk_f16_f32 v174, v156, v157
	v_cvt_pk_f16_f32 v175, v158, v159
	v_cvt_pk_f16_f32 v176, v160, v161
	v_cvt_pk_f16_f32 v177, v162, v163
	global_store_dwordx4 v[172:173], v[174:177], off nt
	global_store_dwordx4 v[182:183], v[174:177], off
	v_lshl_add_u64 v[182:183], v[182:183], 0, s[8:9]
	v_lshl_add_u64 v[172:173], v[172:173], 0, s[12:13]
	s_waitcnt lgkmcnt(0)
	v_pk_mul_f32 v[164:165], v[148:149], s[10:11]
	v_pk_mul_f32 v[166:167], v[150:151], s[10:11]
	v_pk_mul_f32 v[168:169], v[152:153], s[10:11]
	v_pk_mul_f32 v[170:171], v[154:155], s[10:11]
	v_cvt_pk_f16_f32 v174, v164, v165
	v_cvt_pk_f16_f32 v175, v166, v167
	v_cvt_pk_f16_f32 v176, v168, v169
	v_cvt_pk_f16_f32 v177, v170, v171
	global_store_dwordx4 v[172:173], v[174:177], off nt
	global_store_dwordx4 v[182:183], v[174:177], off
	v_lshl_add_u64 v[182:183], v[182:183], 0, s[8:9]
	v_lshl_add_u64 v[172:173], v[172:173], 0, s[12:13]
